# attention: workgroups that finished the RWKV scan (the later-arriving half of each CU pair) run their attention items at priority 1
# baseline (speedup 1.0000x reference)
; #define LAUNDER_IDS const int tid__ = launder_v((int)threadIdx.x); const int blk__ = launder_s((int)blockIdx.x); (void)tid__; (void)blk__;
; DI void phase_scan(const Params& p, char* smem) {
;     ...
;   __builtin_amdgcn_s_setprio(0);
; DI void phase_attn(const Params& p, int l, char* smem) {
;   LAUNDER_IDS
;   __shared__ int qslot_sh;
;   const int nattn = (l == 0) ? 2048 + 128 : 2048;
;   unsigned* ctr = (unsigned*)(p.ws + OFF_BAR) + 16 + l * 16;
;   for (;;) {
.LBB0_516:
	s_setprio 1
	v_readlane_b32 s39, v253, 32
	s_movk_i32 s42, 0x4000
	s_movk_i32 s43, 0x6000
	s_movk_i32 s46, 0xe000
	s_movk_i32 s47, 0x2000

; DI void phase_attn(const Params& p, int l, char* smem) {
;     ...
;   for (;;) {
;     __syncthreads();
;     if (tid__ == 0) qslot_sh = (int)__hip_atomic_fetch_add(ctr, 1u, __ATOMIC_RELAXED, __HIP_MEMORY_SCOPE_AGENT);
;     __syncthreads();
;     const int it = qslot_sh;
;     if (it >= nattn) break;
;     attn_item(p, it, smem);
.LBB0_541:
	s_setprio 0
	s_mov_b64 s[0:1], 0
